# phase-0 weight conversion: only UP/OUT/XQ/XO of layers 2,3 moved into the idle w_in-GEMM workgroups of the previous layer (sized to the idle slot); rest stays in phase 0
# speedup vs baseline: 1.0075x; 1.0075x over previous
; __device__ __forceinline__ int bid_fresh() { int t = blockIdx.x; asm volatile("" : "+s"(t)); return t; }
; __device__ __forceinline__ void phase0(PP p, unsigned char* shm) {
;     ...
;     for (int it = bid_fresh(); it < DEPTH * C_LAYER; it += gridDim.x) {
;         const int l = it / C_LAYER; int r = it % C_LAYER;
;         if (r < C_IN) { tconv_tile_w(p->in[5] + (size_t)l * D * INW, INW, r / 14, r % 14, (bf16_t*)(ws + WS_WIN) + (size_t)l * INW * D, D, tile, p->in[4] + (size_t)l * D); continue; } r -= C_IN;
;         if (r < C_OUT) { tconv_tile_w(p->in[23] + (size_t)l * D * D, D, r / 8, r % 8, (bf16_t*)(ws + WS_WOUT) + (size_t)l * D * D, D, tile, p->in[22] + (size_t)l * D); continue; } r -= C_OUT;
;         if (r < C_XQ) { tconv_tile_w(p->in[25] + (size_t)l * D * 512, 512, r / 2, r % 2, (bf16_t*)(ws + WS_WXQ) + (size_t)l * 512 * D, D, tile, p->in[24] + (size_t)l * D); continue; } r -= C_XQ;
;         if (r < C_XQ) { tconv_tile_w(p->in[26] + (size_t)l * D * 512, 512, r / 2, r % 2, (bf16_t*)(ws + WS_WKV) + (size_t)(l * 1024) * D, D, tile); continue; } r -= C_XQ;
;         if (r < C_XQ) { tconv_tile_w(p->in[27] + (size_t)l * D * 512, 512, r / 2, r % 2, (bf16_t*)(ws + WS_WKV) + (size_t)(l * 1024 + 512) * D, D, tile); continue; } r -= C_XQ;
;         if (r < C_XO) { tconv_tile_w(p->in[28] + (size_t)l * 512 * D, D, r / 8, r % 8, (bf16_t*)(ws + WS_WXO) + (size_t)l * D * 512, 512, tile); continue; } r -= C_XO;
;         if (r < C_UP) { tconv_tile_w(p->in[30] + (size_t)l * D * DFF, DFF, r / 32, r % 32, (bf16_t*)(ws + WS_WUP) + (size_t)l * DFF * D, D, tile, p->in[29] + (size_t)l * D); continue; } r -= C_UP;
;         if (r < C_DN) { if (l == 0) tconv_tile_w(p->in[31] + (size_t)l * DFF * D, D, r / 8, r % 8, (bf16_t*)(ws + WS_WDN) + (size_t)l * D * DFF, DFF, tile); continue; } r -= C_DN;
.LBB0_17:
	s_mov_b64 s[14:15], s[0:1]
	s_load_dwordx2 s[12:13], s[14:15], 0x110
	v_writelane_b32 v254, s26, 2
	s_cmpk_gt_i32 s26, 0x2fbf
	s_cbranch_scc1 .LBB0_71
	s_mov_b32 s27, 0
	s_mov_b32 s28, 0
	s_mov_b32 s29, s26
	s_mov_b32 s63, s66
	s_mov_b32 s64, 0
	s_mov_b32 s65, 4
	s_mov_b32 s84, 0x2667ff
	v_writelane_b32 v255, 0, 62

; __device__ __forceinline__ int bid_fresh() { int t = blockIdx.x; asm volatile("" : "+s"(t)); return t; }
; __global__ void __launch_bounds__(512, 2) hymba_fwd(Params p_unused) {
;     ...
;           { const int G = (int)gridDim.x, c = (int)bid_fresh(), nfull = 448 % G, nidle = (nfull == 0) ? 0 : G - nfull;
;             if (nidle > 0 && c >= nfull) { for (int r = c - nfull; r < 1024; r += nidle)
;                 tconv_tile_w(p->in[31] + (size_t)l * DFF * D, D, r / 8, r % 8, (bf16_t*)(ws + WS_WDN) + (size_t)l * D * DFF, DFF, (float*)shm); }
;             else if (nidle == 0) { for (int r = c; r < 1024; r += G) tconv_tile_w(p->in[31] + (size_t)l * DFF * D, D, r / 8, r % 8, (bf16_t*)(ws + WS_WDN) + (size_t)l * D * DFF, DFF, (float*)shm); } } }
.LBB0_286:
	s_mov_b32 s12, s30
	v_readlane_b32 s2, v254, 52
	s_cmp_lt_i32 s12, s2
	v_readlane_b32 s16, v254, 49
	s_cselect_b64 s[2:3], -1, 0
	v_readlane_b32 s17, v254, 50
	s_or_b64 s[16:17], s[2:3], s[16:17]
	s_mov_b64 s[2:3], -1
	s_and_b64 vcc, exec, s[16:17]
	s_cbranch_vccnz .LBB0_291
	v_readlane_b32 s2, v254, 52
	s_sub_i32 s2, s12, s2
	s_cmpk_gt_i32 s2, 0x3ff
	v_readlane_b32 s24, v255, 17
	v_readlane_b32 s25, v254, 54
	s_movk_i32 s34, 0x404
	s_cbranch_scc1 .LBB0_290
	v_writelane_b32 v124, s2, 0
	v_writelane_b32 v124, s3, 1
	v_writelane_b32 v124, s4, 2
	v_writelane_b32 v124, s5, 3
	v_writelane_b32 v124, s6, 4
	v_writelane_b32 v124, s7, 5
	v_writelane_b32 v124, s12, 6
	v_writelane_b32 v124, s13, 7
	v_writelane_b32 v124, s14, 8
	v_writelane_b32 v124, s15, 9
	v_writelane_b32 v124, s27, 10
	v_writelane_b32 v124, s28, 11
	v_writelane_b32 v124, s29, 12
	v_writelane_b32 v124, s30, 13
	v_writelane_b32 v124, s31, 14
	v_writelane_b32 v124, s33, 15
	v_writelane_b32 v124, s34, 16
	v_writelane_b32 v124, s35, 17
	v_writelane_b32 v124, s36, 18
	v_writelane_b32 v124, s37, 19
	v_writelane_b32 v124, s38, 20
	v_writelane_b32 v124, s39, 21
	v_writelane_b32 v124, s40, 22
	v_writelane_b32 v124, s41, 23
	v_writelane_b32 v124, s42, 24
	v_writelane_b32 v124, s43, 25
	v_writelane_b32 v124, s44, 26
	v_writelane_b32 v124, s45, 27
	v_writelane_b32 v124, s46, 28
	v_writelane_b32 v124, s47, 29
	v_writelane_b32 v124, s48, 30
	v_writelane_b32 v124, s49, 31
	v_writelane_b32 v124, s50, 32
	v_writelane_b32 v124, s51, 33
	v_writelane_b32 v124, s52, 34
	v_writelane_b32 v124, s53, 35
	v_writelane_b32 v124, s54, 36
	v_writelane_b32 v124, s55, 37
	v_writelane_b32 v124, s56, 38
	v_writelane_b32 v124, s57, 39
	v_writelane_b32 v124, s58, 40
	v_writelane_b32 v124, s59, 41
	v_writelane_b32 v124, s60, 42
	v_writelane_b32 v124, s61, 43
	v_writelane_b32 v124, s62, 44
	v_writelane_b32 v124, s63, 45
	v_writelane_b32 v124, s64, 46
	v_writelane_b32 v124, s65, 47
	v_writelane_b32 v124, s68, 48
	v_writelane_b32 v124, s69, 49
	v_writelane_b32 v124, s70, 50
	v_writelane_b32 v124, s71, 51
	v_writelane_b32 v124, s72, 52
	v_writelane_b32 v124, s73, 53
	v_writelane_b32 v124, s74, 54
	v_writelane_b32 v124, s75, 55
	v_writelane_b32 v124, s76, 56
	v_writelane_b32 v124, s77, 57
	v_writelane_b32 v124, s78, 58
	v_writelane_b32 v124, s79, 59
	v_writelane_b32 v124, s80, 60
	v_writelane_b32 v124, s81, 61
	v_writelane_b32 v124, s82, 62
	v_writelane_b32 v124, s83, 63
	v_writelane_b32 v125, s84, 0
	s_mov_b32 s84, 0x99800
	v_readlane_b32 s29, v254, 2
	v_readlane_b32 s3, v254, 52
	v_readlane_b32 s27, v255, 20
	v_readlane_b32 s63, v255, 17
	s_mov_b64 s[14:15], s[0:1]
	s_load_dwordx2 s[12:13], s[0:1], 0x110
	s_nop 3
	s_sub_u32 s29, s29, s3
	s_mov_b32 s28, 9
	s_mov_b32 s64, s27
	s_add_u32 s65, s27, 2
	s_min_u32 s65, s65, 4
	v_writelane_b32 v255, 1, 62
	s_branch .Ltc_entry
